# v19 + RWKV recurrence rescheduled: read-out dots moved into next step DPP gap, V reads and q writes paired with ds_read2st64/ds_write2st64 (6 LDS ops per step)
# speedup vs baseline: 1.0163x; 1.0029x over previous
.LBB0_1238:
	s_or_b64 exec, exec, s[18:19]
	s_waitcnt lgkmcnt(0)
	s_barrier
	s_cmp_lg_u32 s100, 0
	s_cselect_b32 s97, 0x800, 0
	v_add_u32_e32 v167, s97, v114
	ds_read_b128 v[72:75], v114 offset:41216
	ds_read_b128 v[68:71], v114 offset:45312
	ds_read_b128 v[64:67], v114 offset:49408
	ds_read_b128 v[56:59], v114 offset:53504
	ds_read_b128 v[60:63], v167 offset:28928
	ds_read2st64_b32 v[214:215], v115 offset1:1
	s_waitcnt lgkmcnt(0)
	v_dot2_f32_f16 v151, v127, v72, 0
	v_dot2_f32_f16 v151, v126, v73, v151
	v_dot2_f32_f16 v151, v125, v74, v151
	v_dot2_f32_f16 v151, v124, v75, v151
	ds_read_b128 v[134:137], v114 offset:41344
	ds_read_b128 v[138:141], v114 offset:45440
	ds_read_b128 v[142:145], v114 offset:49536
	v_add_f32_dpp v151, v151, v151 quad_perm:[1,0,3,2] row_mask:0xf bank_mask:0xf bound_ctrl:1
	ds_read_b128 v[130:133], v167 offset:29056
	ds_read_b128 v[146:149], v114 offset:53632
	v_add_f32_dpp v151, v151, v151 quad_perm:[2,3,0,1] row_mask:0xf bank_mask:0xf bound_ctrl:1
	s_nop 1
	v_add_f32_dpp v151, v151, v151 row_half_mirror row_mask:0xf bank_mask:0xf bound_ctrl:1
	v_cvt_pkrtz_f16_f32 v152, -v151, -v151
	v_pk_mul_f16 v153, v152, v68
	v_pk_mul_f16 v154, v152, v69
	v_pk_mul_f16 v155, v152, v70
	v_pk_mul_f16 v156, v152, v71
	v_pk_fma_f16 v153, v214, v64, v153
	v_pk_fma_f16 v154, v214, v65, v154
	v_pk_fma_f16 v155, v214, v66, v155
	v_pk_fma_f16 v156, v214, v67, v156
	v_pk_fma_f16 v127, v127, v60, v153
	v_pk_fma_f16 v126, v126, v61, v154
	v_pk_fma_f16 v125, v125, v62, v155
	v_pk_fma_f16 v124, v124, v63, v156
	s_waitcnt lgkmcnt(0)
	v_dot2_f32_f16 v151, v127, v134, 0
	v_dot2_f32_f16 v151, v126, v135, v151
	v_dot2_f32_f16 v151, v125, v136, v151
	v_dot2_f32_f16 v151, v124, v137, v151
	v_dot2_f32_f16 v157, v127, v56, 0
	v_dot2_f32_f16 v157, v126, v57, v157
	v_dot2_f32_f16 v157, v125, v58, v157
	v_dot2_f32_f16 v157, v124, v59, v157
	v_add_f32_dpp v151, v151, v151 quad_perm:[1,0,3,2] row_mask:0xf bank_mask:0xf bound_ctrl:1
	ds_read_b128 v[72:75], v114 offset:41472
	ds_read_b128 v[68:71], v114 offset:45568
	v_add_f32_dpp v151, v151, v151 quad_perm:[2,3,0,1] row_mask:0xf bank_mask:0xf bound_ctrl:1
	ds_read_b128 v[64:67], v114 offset:49664
	ds_read_b128 v[60:63], v167 offset:29184
	ds_read_b128 v[56:59], v114 offset:53760
	ds_read2st64_b32 v[216:217], v115 offset0:2 offset1:3
	v_add_f32_dpp v151, v151, v151 row_half_mirror row_mask:0xf bank_mask:0xf bound_ctrl:1
	v_cvt_pkrtz_f16_f32 v152, -v151, -v151
	v_pk_mul_f16 v153, v152, v138
	v_pk_mul_f16 v154, v152, v139
	v_pk_mul_f16 v155, v152, v140
	v_pk_mul_f16 v156, v152, v141
	v_pk_fma_f16 v153, v215, v142, v153
	v_pk_fma_f16 v154, v215, v143, v154
	v_pk_fma_f16 v155, v215, v144, v155
	v_pk_fma_f16 v156, v215, v145, v156
	v_pk_fma_f16 v127, v127, v130, v153
	v_pk_fma_f16 v126, v126, v131, v154
	v_pk_fma_f16 v125, v125, v132, v155
	v_pk_fma_f16 v124, v124, v133, v156
	s_waitcnt lgkmcnt(0)
	v_dot2_f32_f16 v151, v127, v72, 0
	v_dot2_f32_f16 v151, v126, v73, v151
	v_dot2_f32_f16 v151, v125, v74, v151
	v_dot2_f32_f16 v151, v124, v75, v151
	v_dot2_f32_f16 v158, v127, v146, 0
	v_dot2_f32_f16 v158, v126, v147, v158
	v_dot2_f32_f16 v158, v125, v148, v158
	v_dot2_f32_f16 v158, v124, v149, v158
	v_add_f32_dpp v151, v151, v151 quad_perm:[1,0,3,2] row_mask:0xf bank_mask:0xf bound_ctrl:1
	ds_read_b128 v[134:137], v114 offset:41600
	ds_read_b128 v[138:141], v114 offset:45696
	v_add_f32_dpp v151, v151, v151 quad_perm:[2,3,0,1] row_mask:0xf bank_mask:0xf bound_ctrl:1
	ds_read_b128 v[142:145], v114 offset:49792
	ds_read_b128 v[130:133], v167 offset:29312
	ds_read_b128 v[146:149], v114 offset:53888
	ds_write2st64_b32 v116, v157, v158 offset0:0 offset1:8
	v_add_f32_dpp v151, v151, v151 row_half_mirror row_mask:0xf bank_mask:0xf bound_ctrl:1
	v_cvt_pkrtz_f16_f32 v152, -v151, -v151
	v_pk_mul_f16 v153, v152, v68
	v_pk_mul_f16 v154, v152, v69
	v_pk_mul_f16 v155, v152, v70
	v_pk_mul_f16 v156, v152, v71
	v_pk_fma_f16 v153, v216, v64, v153
	v_pk_fma_f16 v154, v216, v65, v154
	v_pk_fma_f16 v155, v216, v66, v155
	v_pk_fma_f16 v156, v216, v67, v156
	v_pk_fma_f16 v127, v127, v60, v153
	v_pk_fma_f16 v126, v126, v61, v154
	v_pk_fma_f16 v125, v125, v62, v155
	v_pk_fma_f16 v124, v124, v63, v156
	s_waitcnt lgkmcnt(0)
	v_dot2_f32_f16 v151, v127, v134, 0
	v_dot2_f32_f16 v151, v126, v135, v151
	v_dot2_f32_f16 v151, v125, v136, v151
	v_dot2_f32_f16 v151, v124, v137, v151
	v_dot2_f32_f16 v157, v127, v56, 0
	v_dot2_f32_f16 v157, v126, v57, v157
	v_dot2_f32_f16 v157, v125, v58, v157
	v_dot2_f32_f16 v157, v124, v59, v157
	v_add_f32_dpp v151, v151, v151 quad_perm:[1,0,3,2] row_mask:0xf bank_mask:0xf bound_ctrl:1
	ds_read_b128 v[72:75], v114 offset:41728
	ds_read_b128 v[68:71], v114 offset:45824
	v_add_f32_dpp v151, v151, v151 quad_perm:[2,3,0,1] row_mask:0xf bank_mask:0xf bound_ctrl:1
	ds_read_b128 v[64:67], v114 offset:49920
	ds_read_b128 v[60:63], v167 offset:29440
	ds_read_b128 v[56:59], v114 offset:54016
	ds_read2st64_b32 v[214:215], v115 offset0:4 offset1:5
	v_add_f32_dpp v151, v151, v151 row_half_mirror row_mask:0xf bank_mask:0xf bound_ctrl:1
	v_cvt_pkrtz_f16_f32 v152, -v151, -v151
	v_pk_mul_f16 v153, v152, v138
	v_pk_mul_f16 v154, v152, v139
	v_pk_mul_f16 v155, v152, v140
	v_pk_mul_f16 v156, v152, v141
	v_pk_fma_f16 v153, v217, v142, v153
	v_pk_fma_f16 v154, v217, v143, v154
	v_pk_fma_f16 v155, v217, v144, v155
	v_pk_fma_f16 v156, v217, v145, v156
	v_pk_fma_f16 v127, v127, v130, v153
	v_pk_fma_f16 v126, v126, v131, v154
	v_pk_fma_f16 v125, v125, v132, v155
	v_pk_fma_f16 v124, v124, v133, v156
	s_waitcnt lgkmcnt(0)
	v_dot2_f32_f16 v151, v127, v72, 0
	v_dot2_f32_f16 v151, v126, v73, v151
	v_dot2_f32_f16 v151, v125, v74, v151
	v_dot2_f32_f16 v151, v124, v75, v151
	v_dot2_f32_f16 v158, v127, v146, 0
	v_dot2_f32_f16 v158, v126, v147, v158
	v_dot2_f32_f16 v158, v125, v148, v158
	v_dot2_f32_f16 v158, v124, v149, v158
	v_add_f32_dpp v151, v151, v151 quad_perm:[1,0,3,2] row_mask:0xf bank_mask:0xf bound_ctrl:1
	ds_read_b128 v[134:137], v114 offset:41856
	ds_read_b128 v[138:141], v114 offset:45952
	v_add_f32_dpp v151, v151, v151 quad_perm:[2,3,0,1] row_mask:0xf bank_mask:0xf bound_ctrl:1
	ds_read_b128 v[142:145], v114 offset:50048
	ds_read_b128 v[130:133], v167 offset:29568
	ds_read_b128 v[146:149], v114 offset:54144
	ds_write2st64_b32 v116, v157, v158 offset0:16 offset1:24
	v_add_f32_dpp v151, v151, v151 row_half_mirror row_mask:0xf bank_mask:0xf bound_ctrl:1
	v_cvt_pkrtz_f16_f32 v152, -v151, -v151
	v_pk_mul_f16 v153, v152, v68
	v_pk_mul_f16 v154, v152, v69
	v_pk_mul_f16 v155, v152, v70
	v_pk_mul_f16 v156, v152, v71
	v_pk_fma_f16 v153, v214, v64, v153
	v_pk_fma_f16 v154, v214, v65, v154
	v_pk_fma_f16 v155, v214, v66, v155
	v_pk_fma_f16 v156, v214, v67, v156
	v_pk_fma_f16 v127, v127, v60, v153
	v_pk_fma_f16 v126, v126, v61, v154
	v_pk_fma_f16 v125, v125, v62, v155
	v_pk_fma_f16 v124, v124, v63, v156
	s_waitcnt lgkmcnt(0)
	v_dot2_f32_f16 v151, v127, v134, 0
	v_dot2_f32_f16 v151, v126, v135, v151
	v_dot2_f32_f16 v151, v125, v136, v151
	v_dot2_f32_f16 v151, v124, v137, v151
	v_dot2_f32_f16 v157, v127, v56, 0
	v_dot2_f32_f16 v157, v126, v57, v157
	v_dot2_f32_f16 v157, v125, v58, v157
	v_dot2_f32_f16 v157, v124, v59, v157
	v_add_f32_dpp v151, v151, v151 quad_perm:[1,0,3,2] row_mask:0xf bank_mask:0xf bound_ctrl:1
	ds_read_b128 v[72:75], v114 offset:41984
	ds_read_b128 v[68:71], v114 offset:46080
	v_add_f32_dpp v151, v151, v151 quad_perm:[2,3,0,1] row_mask:0xf bank_mask:0xf bound_ctrl:1
	ds_read_b128 v[64:67], v114 offset:50176
	ds_read_b128 v[60:63], v167 offset:29696
	ds_read_b128 v[56:59], v114 offset:54272
	ds_read2st64_b32 v[216:217], v115 offset0:6 offset1:7
	v_add_f32_dpp v151, v151, v151 row_half_mirror row_mask:0xf bank_mask:0xf bound_ctrl:1
	v_cvt_pkrtz_f16_f32 v152, -v151, -v151
	v_pk_mul_f16 v153, v152, v138
	v_pk_mul_f16 v154, v152, v139
	v_pk_mul_f16 v155, v152, v140
	v_pk_mul_f16 v156, v152, v141
	v_pk_fma_f16 v153, v215, v142, v153
	v_pk_fma_f16 v154, v215, v143, v154
	v_pk_fma_f16 v155, v215, v144, v155
	v_pk_fma_f16 v156, v215, v145, v156
	v_pk_fma_f16 v127, v127, v130, v153
	v_pk_fma_f16 v126, v126, v131, v154
	v_pk_fma_f16 v125, v125, v132, v155
	v_pk_fma_f16 v124, v124, v133, v156
	s_waitcnt lgkmcnt(0)
	v_dot2_f32_f16 v151, v127, v72, 0
	v_dot2_f32_f16 v151, v126, v73, v151
	v_dot2_f32_f16 v151, v125, v74, v151
	v_dot2_f32_f16 v151, v124, v75, v151
	v_dot2_f32_f16 v158, v127, v146, 0
	v_dot2_f32_f16 v158, v126, v147, v158
	v_dot2_f32_f16 v158, v125, v148, v158
	v_dot2_f32_f16 v158, v124, v149, v158
	v_add_f32_dpp v151, v151, v151 quad_perm:[1,0,3,2] row_mask:0xf bank_mask:0xf bound_ctrl:1
	ds_read_b128 v[134:137], v114 offset:42112
	ds_read_b128 v[138:141], v114 offset:46208
	v_add_f32_dpp v151, v151, v151 quad_perm:[2,3,0,1] row_mask:0xf bank_mask:0xf bound_ctrl:1
	ds_read_b128 v[142:145], v114 offset:50304
	ds_read_b128 v[130:133], v167 offset:29824
	ds_read_b128 v[146:149], v114 offset:54400
	ds_write2st64_b32 v116, v157, v158 offset0:32 offset1:40
	v_add_f32_dpp v151, v151, v151 row_half_mirror row_mask:0xf bank_mask:0xf bound_ctrl:1
	v_cvt_pkrtz_f16_f32 v152, -v151, -v151
	v_pk_mul_f16 v153, v152, v68
	v_pk_mul_f16 v154, v152, v69
	v_pk_mul_f16 v155, v152, v70
	v_pk_mul_f16 v156, v152, v71
	v_pk_fma_f16 v153, v216, v64, v153
	v_pk_fma_f16 v154, v216, v65, v154
	v_pk_fma_f16 v155, v216, v66, v155
	v_pk_fma_f16 v156, v216, v67, v156
	v_pk_fma_f16 v127, v127, v60, v153
	v_pk_fma_f16 v126, v126, v61, v154
	v_pk_fma_f16 v125, v125, v62, v155
	v_pk_fma_f16 v124, v124, v63, v156
	s_waitcnt lgkmcnt(0)
	v_dot2_f32_f16 v151, v127, v134, 0
	v_dot2_f32_f16 v151, v126, v135, v151
	v_dot2_f32_f16 v151, v125, v136, v151
	v_dot2_f32_f16 v151, v124, v137, v151
	v_dot2_f32_f16 v157, v127, v56, 0
	v_dot2_f32_f16 v157, v126, v57, v157
	v_dot2_f32_f16 v157, v125, v58, v157
	v_dot2_f32_f16 v157, v124, v59, v157
	v_add_f32_dpp v151, v151, v151 quad_perm:[1,0,3,2] row_mask:0xf bank_mask:0xf bound_ctrl:1
	ds_read_b128 v[72:75], v114 offset:42240
	ds_read_b128 v[68:71], v114 offset:46336
	v_add_f32_dpp v151, v151, v151 quad_perm:[2,3,0,1] row_mask:0xf bank_mask:0xf bound_ctrl:1
	ds_read_b128 v[64:67], v114 offset:50432
	ds_read_b128 v[60:63], v167 offset:29952
	ds_read_b128 v[56:59], v114 offset:54528
	ds_read2st64_b32 v[214:215], v115 offset0:8 offset1:9
	v_add_f32_dpp v151, v151, v151 row_half_mirror row_mask:0xf bank_mask:0xf bound_ctrl:1
	v_cvt_pkrtz_f16_f32 v152, -v151, -v151
	v_pk_mul_f16 v153, v152, v138
	v_pk_mul_f16 v154, v152, v139
	v_pk_mul_f16 v155, v152, v140
	v_pk_mul_f16 v156, v152, v141
	v_pk_fma_f16 v153, v217, v142, v153
	v_pk_fma_f16 v154, v217, v143, v154
	v_pk_fma_f16 v155, v217, v144, v155
	v_pk_fma_f16 v156, v217, v145, v156
	v_pk_fma_f16 v127, v127, v130, v153
	v_pk_fma_f16 v126, v126, v131, v154
	v_pk_fma_f16 v125, v125, v132, v155
	v_pk_fma_f16 v124, v124, v133, v156
	s_waitcnt lgkmcnt(0)
	v_dot2_f32_f16 v151, v127, v72, 0
	v_dot2_f32_f16 v151, v126, v73, v151
	v_dot2_f32_f16 v151, v125, v74, v151
	v_dot2_f32_f16 v151, v124, v75, v151
	v_dot2_f32_f16 v158, v127, v146, 0
	v_dot2_f32_f16 v158, v126, v147, v158
	v_dot2_f32_f16 v158, v125, v148, v158
	v_dot2_f32_f16 v158, v124, v149, v158
	v_add_f32_dpp v151, v151, v151 quad_perm:[1,0,3,2] row_mask:0xf bank_mask:0xf bound_ctrl:1
	ds_read_b128 v[134:137], v114 offset:42368
	ds_read_b128 v[138:141], v114 offset:46464
	v_add_f32_dpp v151, v151, v151 quad_perm:[2,3,0,1] row_mask:0xf bank_mask:0xf bound_ctrl:1
	ds_read_b128 v[142:145], v114 offset:50560
	ds_read_b128 v[130:133], v167 offset:30080
	ds_read_b128 v[146:149], v114 offset:54656
	ds_write2st64_b32 v116, v157, v158 offset0:48 offset1:56
	v_add_f32_dpp v151, v151, v151 row_half_mirror row_mask:0xf bank_mask:0xf bound_ctrl:1
	v_cvt_pkrtz_f16_f32 v152, -v151, -v151
	v_pk_mul_f16 v153, v152, v68
	v_pk_mul_f16 v154, v152, v69
	v_pk_mul_f16 v155, v152, v70
	v_pk_mul_f16 v156, v152, v71
	v_pk_fma_f16 v153, v214, v64, v153
	v_pk_fma_f16 v154, v214, v65, v154
	v_pk_fma_f16 v155, v214, v66, v155
	v_pk_fma_f16 v156, v214, v67, v156
	v_pk_fma_f16 v127, v127, v60, v153
	v_pk_fma_f16 v126, v126, v61, v154
	v_pk_fma_f16 v125, v125, v62, v155
	v_pk_fma_f16 v124, v124, v63, v156
	s_waitcnt lgkmcnt(0)
	v_dot2_f32_f16 v151, v127, v134, 0
	v_dot2_f32_f16 v151, v126, v135, v151
	v_dot2_f32_f16 v151, v125, v136, v151
	v_dot2_f32_f16 v151, v124, v137, v151
	v_dot2_f32_f16 v157, v127, v56, 0
	v_dot2_f32_f16 v157, v126, v57, v157
	v_dot2_f32_f16 v157, v125, v58, v157
	v_dot2_f32_f16 v157, v124, v59, v157
	v_add_f32_dpp v151, v151, v151 quad_perm:[1,0,3,2] row_mask:0xf bank_mask:0xf bound_ctrl:1
	ds_read_b128 v[72:75], v114 offset:42496
	ds_read_b128 v[68:71], v114 offset:46592
	v_add_f32_dpp v151, v151, v151 quad_perm:[2,3,0,1] row_mask:0xf bank_mask:0xf bound_ctrl:1
	ds_read_b128 v[64:67], v114 offset:50688
	ds_read_b128 v[60:63], v167 offset:30208
	ds_read_b128 v[56:59], v114 offset:54784
	ds_read2st64_b32 v[216:217], v115 offset0:10 offset1:11
	v_add_f32_dpp v151, v151, v151 row_half_mirror row_mask:0xf bank_mask:0xf bound_ctrl:1
	v_cvt_pkrtz_f16_f32 v152, -v151, -v151
	v_pk_mul_f16 v153, v152, v138
	v_pk_mul_f16 v154, v152, v139
	v_pk_mul_f16 v155, v152, v140
	v_pk_mul_f16 v156, v152, v141
	v_pk_fma_f16 v153, v215, v142, v153
	v_pk_fma_f16 v154, v215, v143, v154
	v_pk_fma_f16 v155, v215, v144, v155
	v_pk_fma_f16 v156, v215, v145, v156
	v_pk_fma_f16 v127, v127, v130, v153
	v_pk_fma_f16 v126, v126, v131, v154
	v_pk_fma_f16 v125, v125, v132, v155
	v_pk_fma_f16 v124, v124, v133, v156
	s_waitcnt lgkmcnt(0)
	v_dot2_f32_f16 v151, v127, v72, 0
	v_dot2_f32_f16 v151, v126, v73, v151
	v_dot2_f32_f16 v151, v125, v74, v151
	v_dot2_f32_f16 v151, v124, v75, v151
	v_dot2_f32_f16 v158, v127, v146, 0
	v_dot2_f32_f16 v158, v126, v147, v158
	v_dot2_f32_f16 v158, v125, v148, v158
	v_dot2_f32_f16 v158, v124, v149, v158
	v_add_f32_dpp v151, v151, v151 quad_perm:[1,0,3,2] row_mask:0xf bank_mask:0xf bound_ctrl:1
	ds_read_b128 v[134:137], v114 offset:42624
	ds_read_b128 v[138:141], v114 offset:46720
	v_add_f32_dpp v151, v151, v151 quad_perm:[2,3,0,1] row_mask:0xf bank_mask:0xf bound_ctrl:1
	ds_read_b128 v[142:145], v114 offset:50816
	ds_read_b128 v[130:133], v167 offset:30336
	ds_read_b128 v[146:149], v114 offset:54912
	ds_write2st64_b32 v116, v157, v158 offset0:64 offset1:72
	v_add_f32_dpp v151, v151, v151 row_half_mirror row_mask:0xf bank_mask:0xf bound_ctrl:1
	v_cvt_pkrtz_f16_f32 v152, -v151, -v151
	v_pk_mul_f16 v153, v152, v68
	v_pk_mul_f16 v154, v152, v69
	v_pk_mul_f16 v155, v152, v70
	v_pk_mul_f16 v156, v152, v71
	v_pk_fma_f16 v153, v216, v64, v153
	v_pk_fma_f16 v154, v216, v65, v154
	v_pk_fma_f16 v155, v216, v66, v155
	v_pk_fma_f16 v156, v216, v67, v156
	v_pk_fma_f16 v127, v127, v60, v153
	v_pk_fma_f16 v126, v126, v61, v154
	v_pk_fma_f16 v125, v125, v62, v155
	v_pk_fma_f16 v124, v124, v63, v156
	s_waitcnt lgkmcnt(0)
	v_dot2_f32_f16 v151, v127, v134, 0
	v_dot2_f32_f16 v151, v126, v135, v151
	v_dot2_f32_f16 v151, v125, v136, v151
	v_dot2_f32_f16 v151, v124, v137, v151
	v_dot2_f32_f16 v157, v127, v56, 0
	v_dot2_f32_f16 v157, v126, v57, v157
	v_dot2_f32_f16 v157, v125, v58, v157
	v_dot2_f32_f16 v157, v124, v59, v157
	v_add_f32_dpp v151, v151, v151 quad_perm:[1,0,3,2] row_mask:0xf bank_mask:0xf bound_ctrl:1
	ds_read_b128 v[72:75], v114 offset:42752
	ds_read_b128 v[68:71], v114 offset:46848
	v_add_f32_dpp v151, v151, v151 quad_perm:[2,3,0,1] row_mask:0xf bank_mask:0xf bound_ctrl:1
	ds_read_b128 v[64:67], v114 offset:50944
	ds_read_b128 v[60:63], v167 offset:30464
	ds_read_b128 v[56:59], v114 offset:55040
	ds_read2st64_b32 v[214:215], v115 offset0:12 offset1:13
	v_add_f32_dpp v151, v151, v151 row_half_mirror row_mask:0xf bank_mask:0xf bound_ctrl:1
	v_cvt_pkrtz_f16_f32 v152, -v151, -v151
	v_pk_mul_f16 v153, v152, v138
	v_pk_mul_f16 v154, v152, v139
	v_pk_mul_f16 v155, v152, v140
	v_pk_mul_f16 v156, v152, v141
	v_pk_fma_f16 v153, v217, v142, v153
	v_pk_fma_f16 v154, v217, v143, v154
	v_pk_fma_f16 v155, v217, v144, v155
	v_pk_fma_f16 v156, v217, v145, v156
	v_pk_fma_f16 v127, v127, v130, v153
	v_pk_fma_f16 v126, v126, v131, v154
	v_pk_fma_f16 v125, v125, v132, v155
	v_pk_fma_f16 v124, v124, v133, v156
	s_waitcnt lgkmcnt(0)
	v_dot2_f32_f16 v151, v127, v72, 0
	v_dot2_f32_f16 v151, v126, v73, v151
	v_dot2_f32_f16 v151, v125, v74, v151
	v_dot2_f32_f16 v151, v124, v75, v151
	v_dot2_f32_f16 v158, v127, v146, 0
	v_dot2_f32_f16 v158, v126, v147, v158
	v_dot2_f32_f16 v158, v125, v148, v158
	v_dot2_f32_f16 v158, v124, v149, v158
	v_add_f32_dpp v151, v151, v151 quad_perm:[1,0,3,2] row_mask:0xf bank_mask:0xf bound_ctrl:1
	ds_read_b128 v[134:137], v114 offset:42880
	ds_read_b128 v[138:141], v114 offset:46976
	v_add_f32_dpp v151, v151, v151 quad_perm:[2,3,0,1] row_mask:0xf bank_mask:0xf bound_ctrl:1
	ds_read_b128 v[142:145], v114 offset:51072
	ds_read_b128 v[130:133], v167 offset:30592
	ds_read_b128 v[146:149], v114 offset:55168
	ds_write2st64_b32 v116, v157, v158 offset0:80 offset1:88
	v_add_f32_dpp v151, v151, v151 row_half_mirror row_mask:0xf bank_mask:0xf bound_ctrl:1
	v_cvt_pkrtz_f16_f32 v152, -v151, -v151
	v_pk_mul_f16 v153, v152, v68
	v_pk_mul_f16 v154, v152, v69
	v_pk_mul_f16 v155, v152, v70
	v_pk_mul_f16 v156, v152, v71
	v_pk_fma_f16 v153, v214, v64, v153
	v_pk_fma_f16 v154, v214, v65, v154
	v_pk_fma_f16 v155, v214, v66, v155
	v_pk_fma_f16 v156, v214, v67, v156
	v_pk_fma_f16 v127, v127, v60, v153
	v_pk_fma_f16 v126, v126, v61, v154
	v_pk_fma_f16 v125, v125, v62, v155
	v_pk_fma_f16 v124, v124, v63, v156
	s_waitcnt lgkmcnt(0)
	v_dot2_f32_f16 v151, v127, v134, 0
	v_dot2_f32_f16 v151, v126, v135, v151
	v_dot2_f32_f16 v151, v125, v136, v151
	v_dot2_f32_f16 v151, v124, v137, v151
	v_dot2_f32_f16 v157, v127, v56, 0
	v_dot2_f32_f16 v157, v126, v57, v157
	v_dot2_f32_f16 v157, v125, v58, v157
	v_dot2_f32_f16 v157, v124, v59, v157
	v_add_f32_dpp v151, v151, v151 quad_perm:[1,0,3,2] row_mask:0xf bank_mask:0xf bound_ctrl:1
	ds_read_b128 v[72:75], v114 offset:43008
	ds_read_b128 v[68:71], v114 offset:47104
	v_add_f32_dpp v151, v151, v151 quad_perm:[2,3,0,1] row_mask:0xf bank_mask:0xf bound_ctrl:1
	ds_read_b128 v[64:67], v114 offset:51200
	ds_read_b128 v[60:63], v167 offset:30720
	ds_read_b128 v[56:59], v114 offset:55296
	ds_read2st64_b32 v[216:217], v115 offset0:14 offset1:15
	v_add_f32_dpp v151, v151, v151 row_half_mirror row_mask:0xf bank_mask:0xf bound_ctrl:1
	v_cvt_pkrtz_f16_f32 v152, -v151, -v151
	v_pk_mul_f16 v153, v152, v138
	v_pk_mul_f16 v154, v152, v139
	v_pk_mul_f16 v155, v152, v140
	v_pk_mul_f16 v156, v152, v141
	v_pk_fma_f16 v153, v215, v142, v153
	v_pk_fma_f16 v154, v215, v143, v154
	v_pk_fma_f16 v155, v215, v144, v155
	v_pk_fma_f16 v156, v215, v145, v156
	v_pk_fma_f16 v127, v127, v130, v153
	v_pk_fma_f16 v126, v126, v131, v154
	v_pk_fma_f16 v125, v125, v132, v155
	v_pk_fma_f16 v124, v124, v133, v156
	s_waitcnt lgkmcnt(0)
	v_dot2_f32_f16 v151, v127, v72, 0
	v_dot2_f32_f16 v151, v126, v73, v151
	v_dot2_f32_f16 v151, v125, v74, v151
	v_dot2_f32_f16 v151, v124, v75, v151
	v_dot2_f32_f16 v158, v127, v146, 0
	v_dot2_f32_f16 v158, v126, v147, v158
	v_dot2_f32_f16 v158, v125, v148, v158
	v_dot2_f32_f16 v158, v124, v149, v158
	v_add_f32_dpp v151, v151, v151 quad_perm:[1,0,3,2] row_mask:0xf bank_mask:0xf bound_ctrl:1
	ds_read_b128 v[134:137], v114 offset:43136
	ds_read_b128 v[138:141], v114 offset:47232
	v_add_f32_dpp v151, v151, v151 quad_perm:[2,3,0,1] row_mask:0xf bank_mask:0xf bound_ctrl:1
	ds_read_b128 v[142:145], v114 offset:51328
	ds_read_b128 v[130:133], v167 offset:30848
	ds_read_b128 v[146:149], v114 offset:55424
	ds_write2st64_b32 v116, v157, v158 offset0:96 offset1:104
	v_add_f32_dpp v151, v151, v151 row_half_mirror row_mask:0xf bank_mask:0xf bound_ctrl:1
	v_cvt_pkrtz_f16_f32 v152, -v151, -v151
	v_pk_mul_f16 v153, v152, v68
	v_pk_mul_f16 v154, v152, v69
	v_pk_mul_f16 v155, v152, v70
	v_pk_mul_f16 v156, v152, v71
	v_pk_fma_f16 v153, v216, v64, v153
	v_pk_fma_f16 v154, v216, v65, v154
	v_pk_fma_f16 v155, v216, v66, v155
	v_pk_fma_f16 v156, v216, v67, v156
	v_pk_fma_f16 v127, v127, v60, v153
	v_pk_fma_f16 v126, v126, v61, v154
	v_pk_fma_f16 v125, v125, v62, v155
	v_pk_fma_f16 v124, v124, v63, v156
	s_waitcnt lgkmcnt(0)
	v_dot2_f32_f16 v151, v127, v134, 0
	v_dot2_f32_f16 v151, v126, v135, v151
	v_dot2_f32_f16 v151, v125, v136, v151
	v_dot2_f32_f16 v151, v124, v137, v151
	v_dot2_f32_f16 v157, v127, v56, 0
	v_dot2_f32_f16 v157, v126, v57, v157
	v_dot2_f32_f16 v157, v125, v58, v157
	v_dot2_f32_f16 v157, v124, v59, v157
	v_add_f32_dpp v151, v151, v151 quad_perm:[1,0,3,2] row_mask:0xf bank_mask:0xf bound_ctrl:1
	s_nop 1
	v_add_f32_dpp v151, v151, v151 quad_perm:[2,3,0,1] row_mask:0xf bank_mask:0xf bound_ctrl:1
	s_nop 1
	v_add_f32_dpp v151, v151, v151 row_half_mirror row_mask:0xf bank_mask:0xf bound_ctrl:1
	v_cvt_pkrtz_f16_f32 v152, -v151, -v151
	v_pk_mul_f16 v153, v152, v138
	v_pk_mul_f16 v154, v152, v139
	v_pk_mul_f16 v155, v152, v140
	v_pk_mul_f16 v156, v152, v141
	v_pk_fma_f16 v153, v217, v142, v153
	v_pk_fma_f16 v154, v217, v143, v154
	v_pk_fma_f16 v155, v217, v144, v155
	v_pk_fma_f16 v156, v217, v145, v156
	v_pk_fma_f16 v127, v127, v130, v153
	v_pk_fma_f16 v126, v126, v131, v154
	v_pk_fma_f16 v125, v125, v132, v155
	v_pk_fma_f16 v124, v124, v133, v156
	v_dot2_f32_f16 v158, v127, v146, 0
	v_dot2_f32_f16 v158, v126, v147, v158
	v_dot2_f32_f16 v158, v125, v148, v158
	v_dot2_f32_f16 v158, v124, v149, v158
	s_nop 2
	ds_write2st64_b32 v116, v157, v158 offset0:112 offset1:120
	s_xor_b32 s100, s100, 0xe100
	s_cmpk_lg_i32 s30, 0x80
	s_cbranch_scc0 .LBB0_1250
	s_mov_b32 s4, s30
	s_and_saveexec_b64 s[18:19], s[10:11]
	s_cbranch_execnz .LBB0_1229
	s_branch .LBB0_1230
